# own-block merge epilogue: L2 warm-up touch loads for the remaining rows partial-O/lse/mask reads
# speedup vs baseline: 1.0050x; 1.0050x over previous
; __device__ __forceinline__ int crow(int r,int hi){return (r&3)+8*(r>>2)+4*hi;}
; template<int THRL,int KIND> __device__ __forceinline__ void attn_unit(const bf16*Qlane,const bf16*__restrict__ Kh,const bf16*__restrict__ Vh,const int NT,const int NTs,char*shm,const float*cbh,const unsigned selw_in,const float*relb,const int h,bf16*Odirect,const int pidx,bf16*PO,float*PL,const int ...
;     ...
;   float rli[16];
;   #pragma unroll
;   for(int r=0;r<16;++r)rli[r]=__builtin_amdgcn_rcpf(wsf[32+crow(r,hi)]);
;   typedef __attribute__((address_space(3))) int lds_i32; lds_i32* const dstt=(lds_i32*)(shm3+LDS_CB)+wid*32;
;   if constexpr(KIND==2){ if(hi==0){ dstt[r32]=pidx; if(pidx>=0) PL[pidx]=mhat+__builtin_log2f(l_reg); } }
;   if constexpr(KIND==1){ if(hi==0) wsf[r32]=mhat+__builtin_log2f(l_reg); }
;   { bf16*stg=(bf16*)(shm+LDS_OST)+wid*2048;
;     #pragma unroll
;     for(int r=0;r<16;++r){const int orow=crow(r,hi);
;       #pragma unroll
;       for(int d0=0;d0<2;++d0)stg[orow*64+d0*32+r32]=__float2bfloat16(o[d0][r]*rli[r]);}
;     asm volatile("s_waitcnt lgkmcnt(0)":::"memory");
;     #pragma unroll
;     for(int i=0;i<4;++i){const int row=i*8+(lane>>3),ch=lane&7; const u32x4 v=*(const u32x4*)(stg+row*64+ch*8);
.LBB0_1067:
	s_or_b64 exec, exec, s[40:41]
	s_ashr_i32 s37, s36, 31
	s_lshl_b64 s[8:9], s[36:37], 15
	s_add_u32 s8, s15, s8
	s_waitcnt lgkmcnt(3)
	v_rcp_f32_e32 v44, v44
	s_addc_u32 s9, s16, s9
	s_lshl_b32 s13, s21, 2
	s_add_u32 s38, s8, s13
	s_addc_u32 s39, s9, 0
	s_lshl_b32 s8, s36, 13
	s_lshl_b32 s9, s22, 12
	v_rcp_f32_e32 v45, v45
	s_or_b32 s8, s8, s21
	s_add_i32 s21, s9, 0
	v_lshl_add_u32 v48, v176, 1, s21
	v_mul_f32_e32 v0, v0, v44
	v_lshl_add_u32 v49, v182, 9, v48
	v_cvt_pk_bf16_f32 v0, v0, s0
	ds_write_b16 v49, v0 offset:51200
	v_mul_f32_e32 v0, v16, v44
	v_rcp_f32_e32 v46, v46
	v_cvt_pk_bf16_f32 v0, v0, s0
	v_mul_f32_e32 v1, v1, v45
	ds_write_b16 v49, v0 offset:51264
	v_lshl_add_u32 v0, v183, 7, v48
	v_cvt_pk_bf16_f32 v1, v1, s0
	ds_write_b16 v0, v1 offset:51200
	v_mul_f32_e32 v1, v17, v45
	v_cvt_pk_bf16_f32 v1, v1, s0
	v_rcp_f32_e32 v47, v47
	ds_write_b16 v0, v1 offset:51264
	v_mul_f32_e32 v1, v2, v46
	v_lshl_add_u32 v0, v184, 7, v48
	v_cvt_pk_bf16_f32 v1, v1, s0
	ds_write_b16 v0, v1 offset:51200
	v_mul_f32_e32 v1, v18, v46
	v_cvt_pk_bf16_f32 v1, v1, s0
	s_waitcnt lgkmcnt(7)
	v_rcp_f32_e32 v40, v40
	ds_write_b16 v0, v1 offset:51264
	v_mul_f32_e32 v1, v3, v47
	v_lshl_add_u32 v0, v185, 7, v48
	v_cvt_pk_bf16_f32 v1, v1, s0
	ds_write_b16 v0, v1 offset:51200
	v_mul_f32_e32 v1, v19, v47
	v_cvt_pk_bf16_f32 v1, v1, s0
	v_rcp_f32_e32 v41, v41
	ds_write_b16 v0, v1 offset:51264
	v_mul_f32_e32 v1, v4, v40
	v_lshl_add_u32 v0, v186, 7, v48
	v_cvt_pk_bf16_f32 v1, v1, s0
	ds_write_b16 v0, v1 offset:51200
	v_mul_f32_e32 v1, v20, v40
	v_cvt_pk_bf16_f32 v1, v1, s0
	v_rcp_f32_e32 v42, v42
	ds_write_b16 v0, v1 offset:51264
	v_mul_f32_e32 v1, v5, v41
	v_lshl_add_u32 v0, v187, 7, v48
	v_cvt_pk_bf16_f32 v1, v1, s0
	ds_write_b16 v0, v1 offset:51200
	v_mul_f32_e32 v1, v21, v41
	v_cvt_pk_bf16_f32 v1, v1, s0
	v_rcp_f32_e32 v43, v43
	ds_write_b16 v0, v1 offset:51264
	v_mul_f32_e32 v1, v6, v42
	v_lshl_add_u32 v0, v189, 7, v48
	v_cvt_pk_bf16_f32 v1, v1, s0
	ds_write_b16 v0, v1 offset:51200
	v_mul_f32_e32 v1, v22, v42
	v_cvt_pk_bf16_f32 v1, v1, s0
	s_waitcnt lgkmcnt(14)
	v_rcp_f32_e32 v36, v36
	ds_write_b16 v0, v1 offset:51264
	v_mul_f32_e32 v1, v7, v43
	v_lshl_add_u32 v0, v190, 7, v48
	v_cvt_pk_bf16_f32 v1, v1, s0
	ds_write_b16 v0, v1 offset:51200
	v_mul_f32_e32 v1, v23, v43
	v_cvt_pk_bf16_f32 v1, v1, s0
	v_rcp_f32_e32 v37, v37
	ds_write_b16 v0, v1 offset:51264
	v_mul_f32_e32 v1, v8, v36
	v_lshl_add_u32 v0, v191, 7, v48
	v_cvt_pk_bf16_f32 v1, v1, s0
	ds_write_b16 v0, v1 offset:51200
	v_mul_f32_e32 v1, v24, v36
	v_cvt_pk_bf16_f32 v1, v1, s0
	v_rcp_f32_e32 v38, v38
	ds_write_b16 v0, v1 offset:51264
	v_mul_f32_e32 v1, v9, v37
	v_lshl_add_u32 v0, v192, 7, v48
	v_cvt_pk_bf16_f32 v1, v1, s0
	ds_write_b16 v0, v1 offset:51200
	v_mul_f32_e32 v1, v25, v37
	v_cvt_pk_bf16_f32 v1, v1, s0
	v_rcp_f32_e32 v39, v39
	ds_write_b16 v0, v1 offset:51264
	v_mul_f32_e32 v1, v10, v38
	v_lshl_add_u32 v0, v193, 7, v48
	v_cvt_pk_bf16_f32 v1, v1, s0
	ds_write_b16 v0, v1 offset:51200
	v_mul_f32_e32 v1, v26, v38
	v_cvt_pk_bf16_f32 v1, v1, s0
	s_waitcnt lgkmcnt(14)
	v_rcp_f32_e32 v32, v32
	ds_write_b16 v0, v1 offset:51264
	v_mul_f32_e32 v1, v11, v39
	v_lshl_add_u32 v0, v194, 7, v48
	v_cvt_pk_bf16_f32 v1, v1, s0
	ds_write_b16 v0, v1 offset:51200
	v_mul_f32_e32 v1, v27, v39
	v_cvt_pk_bf16_f32 v1, v1, s0
	v_rcp_f32_e32 v33, v33
	ds_write_b16 v0, v1 offset:51264
	v_mul_f32_e32 v1, v12, v32
	v_lshl_add_u32 v0, v195, 7, v48
	v_cvt_pk_bf16_f32 v1, v1, s0
	ds_write_b16 v0, v1 offset:51200
	v_mul_f32_e32 v1, v28, v32
	v_cvt_pk_bf16_f32 v1, v1, s0
	v_rcp_f32_e32 v34, v34
	ds_write_b16 v0, v1 offset:51264
	v_mul_f32_e32 v1, v13, v33
	v_lshl_add_u32 v0, v196, 7, v48
	v_cvt_pk_bf16_f32 v1, v1, s0
	ds_write_b16 v0, v1 offset:51200
	v_mul_f32_e32 v1, v29, v33
	v_cvt_pk_bf16_f32 v1, v1, s0
	v_rcp_f32_e32 v35, v35
	ds_write_b16 v0, v1 offset:51264
	v_mul_f32_e32 v1, v14, v34
	v_lshl_add_u32 v0, v197, 7, v48
	v_cvt_pk_bf16_f32 v1, v1, s0
	ds_write_b16 v0, v1 offset:51200
	v_mul_f32_e32 v1, v30, v34
	v_cvt_pk_bf16_f32 v1, v1, s0
	ds_write_b16 v0, v1 offset:51264
	v_mul_f32_e32 v1, v15, v35
	v_lshl_add_u32 v0, v198, 7, v48
	v_cvt_pk_bf16_f32 v1, v1, s0
	ds_write_b16 v0, v1 offset:51200
	v_mul_f32_e32 v1, v31, v35
	v_cvt_pk_bf16_f32 v1, v1, s0
	v_lshrrev_b32_e32 v176, 3, v181
	s_ashr_i32 s9, s8, 31
	s_ashr_i32 s13, s12, 31
	ds_write_b16 v0, v1 offset:51264
	s_add_u32 s8, s12, s8
	v_or_b32_e32 v0, s12, v176
	s_addc_u32 s9, s13, s9
	v_ashrrev_i32_e32 v1, 31, v0
	s_waitcnt lgkmcnt(0)
; template<int THRL,int KIND> __device__ __forceinline__ void attn_unit(const bf16*Qlane,const bf16*__restrict__ Kh,const bf16*__restrict__ Vh,const int NT,const int NTs,char*shm,const float*cbh,const unsigned selw_in,const float*relb,const int h,bf16*Odirect,const int pidx,bf16*PO,float*PL,const int ...
;     ...
;     for(int i=0;i<4;++i){const int row=i*8+(lane>>3),ch=lane&7; const u32x4 v=*(const u32x4*)(stg+row*64+ch*8);
;       if constexpr(KIND==0){ ATTN_STORE16(Odirect+(long)row*DM+ch*8,v); }
;       else if constexpr(KIND==2){ const int d_=dstt[row]; if(d_>=0) ATTN_STORE16(PO+(long)d_*64+ch*8,v); }
;       else { const long ridx=(long)pidx+wid*32+row; const unsigned sm_=((const unsigned*)cbh)[wid*32+row]; const int np=__builtin_popcount(sm_&~(1u<<trel));
;         const f32x4v l4=*(const f32x4v*)(PL+ridx*4); const float l0=wsf[row];
;         float mx=l0; if(np>0)mx=__builtin_fmaxf(mx,l4[1]); if(np>1)mx=__builtin_fmaxf(mx,l4[2]); if(np>2)mx=__builtin_fmaxf(mx,l4[3]);
;         const float w0=__builtin_amdgcn_exp2f(l0-mx); float wsum=w0; float ac[8];
;         ac[0]=w0*__uint_as_float(v[0]<<16); ac[1]=w0*__uint_as_float(v[0]&0xffff0000u); ac[2]=w0*__uint_as_float(v[1]<<16); ac[3]=w0*__uint_as_float(v[1]&0xffff0000u);
;         ac[4]=w0*__uint_as_float(v[2]<<16); ac[5]=w0*__uint_as_float(v[2]&0xffff0000u); ac[6]=w0*__uint_as_float(v[3]<<16); ac[7]=w0*__uint_as_float(v[3]&0xffff0000u);
;         #pragma unroll
;         for(int s_=1;s_<4;++s_) if(s_<=np){ const float ws_=__builtin_amdgcn_exp2f(l4[s_]-mx); wsum+=ws_; const u32x4 p=*(const u32x4*)(PO+(ridx*4+s_)*64+ch*8);
;           ac[0]+=ws_*__uint_as_float(p[0]<<16); ac[1]+=ws_*__uint_as_float(p[0]&0xffff0000u); ac[2]+=ws_*__uint_as_float(p[1]<<16); ac[3]+=ws_*__uint_as_float(p[1]&0xffff0000u);
;           ac[4]+=ws_*__uint_as_float(p[2]<<16); ac[5]+=ws_*__uint_as_float(p[2]&0xffff0000u); ac[6]+=ws_*__uint_as_float(p[3]<<16); ac[7]+=ws_*__uint_as_float(p[3]&0xffff0000u); }
	v_or_b32_e32 v16, s8, v176
	v_mov_b32_e32 v17, s9
	v_lshl_add_u64 v[0:1], v[0:1], 2, s[38:39]
	global_load_dword v8, v[0:1], off
	v_lshl_add_u64 v[0:1], v[16:17], 4, s[28:29]
	global_load_dwordx4 v[0:3], v[0:1], off
	s_waitcnt vmcnt(0)
	v_and_b32_e32 v0, 56, v180
	v_lshlrev_b32_e32 v6, 1, v0
	v_add_u32_e32 v20, s21, v6
	v_lshl_add_u32 v0, v176, 7, v20
	v_lshl_add_u32 v21, v176, 2, s70
	ds_read_b128 v[12:15], v0 offset:51200
	ds_read_b32 v0, v21 offset:49152
	s_lshl_b32 s20, 1, s20
	v_mov_b32_e32 v7, v177
	v_lshl_add_u64 v[4:5], s[4:5], 0, v[6:7]
	v_lshlrev_b64 v[16:17], 9, v[16:17]
	s_waitcnt lgkmcnt(0)
	v_max_f32_e32 v10, v0, v0
	v_lshl_add_u64 v[16:17], v[4:5], 0, v[16:17]
	global_load_dword v244, v[16:17], off offset:128
	global_load_dword v244, v[16:17], off offset:256
	global_load_dword v244, v[16:17], off offset:384
	s_mov_b32 s99, 0
	s_movk_i32 s98, 0x1000
	v_lshl_add_u64 v[240:241], v[16:17], 0, s[98:99]
	global_load_dword v244, v[240:241], off offset:128
	global_load_dword v244, v[240:241], off offset:256
	global_load_dword v244, v[240:241], off offset:384
	s_movk_i32 s98, 0x2000
	v_lshl_add_u64 v[240:241], v[16:17], 0, s[98:99]
	global_load_dword v244, v[240:241], off offset:128
	global_load_dword v244, v[240:241], off offset:256
	global_load_dword v244, v[240:241], off offset:384
	s_movk_i32 s98, 0x3000
	v_lshl_add_u64 v[240:241], v[16:17], 0, s[98:99]
	global_load_dword v244, v[240:241], off offset:128
	global_load_dword v244, v[240:241], off offset:256
	global_load_dword v244, v[240:241], off offset:384
	v_or_b32_e32 v242, s8, v176
	v_mov_b32_e32 v243, s9
	v_lshl_add_u64 v[242:243], v[242:243], 4, s[28:29]
	global_load_dword v244, v[242:243], off offset:128
	global_load_dword v244, v[242:243], off offset:256
	global_load_dword v244, v[242:243], off offset:384
	v_lshl_add_u64 v[242:243], v[176:177], 0, s[12:13]
	v_lshl_add_u64 v[242:243], v[242:243], 2, s[38:39]
	global_load_dword v244, v[242:243], off offset:32
	global_load_dword v244, v[242:243], off offset:64
	global_load_dword v244, v[242:243], off offset:96
	v_bitop3_b32 v8, v8, s20, v8 bitop3:0x30
	v_cmp_eq_u32_e32 vcc, 0, v8
	v_max_f32_e32 v9, v1, v1
	v_max_f32_e32 v9, v10, v9
	v_cndmask_b32_e32 v9, v9, v0, vcc
	v_bcnt_u32_b32 v7, v8, 0
	v_max_f32_e32 v10, v9, v9
	v_max_f32_e32 v11, v2, v2
	v_max_f32_e32 v10, v10, v11
	v_cmp_lt_u32_e32 vcc, 1, v7
	v_max_f32_e32 v11, v3, v3
	s_nop 0
	v_cndmask_b32_e32 v9, v9, v10, vcc
	v_max_f32_e32 v10, v9, v9
	v_max_f32_e32 v18, v10, v11
	v_cmp_lt_u32_e32 vcc, 2, v7
	v_and_b32_e32 v10, 0xffff0000, v13
	v_lshlrev_b32_e32 v11, 16, v13
	v_cndmask_b32_e32 v19, v9, v18, vcc
	v_sub_f32_e32 v0, v0, v19
	v_exp_f32_e32 v0, v0
	v_cmp_ne_u32_e32 vcc, 0, v8
	v_and_b32_e32 v8, 0xffff0000, v12
	v_lshlrev_b32_e32 v9, 16, v12
	v_and_b32_e32 v12, 0xffff0000, v14
	v_lshlrev_b32_e32 v13, 16, v14
	v_and_b32_e32 v14, 0xffff0000, v15
	v_lshlrev_b32_e32 v15, 16, v15
	v_pk_mul_f32 v[8:9], v[0:1], v[8:9] op_sel_hi:[0,1]
	v_pk_mul_f32 v[10:11], v[0:1], v[10:11] op_sel_hi:[0,1]
	v_pk_mul_f32 v[12:13], v[0:1], v[12:13] op_sel_hi:[0,1]
	v_pk_mul_f32 v[14:15], v[0:1], v[14:15] op_sel_hi:[0,1]
	s_and_saveexec_b64 s[36:37], vcc
	s_cbranch_execz .LBB0_1069
	global_load_dwordx4 v[22:25], v[16:17], off offset:128
	v_sub_f32_e32 v1, v1, v19
	v_exp_f32_e32 v26, v1
	s_waitcnt vmcnt(0)
	v_and_b32_e32 v28, 0xffff0000, v22
	v_lshlrev_b32_e32 v29, 16, v22
	v_and_b32_e32 v22, 0xffff0000, v23
	v_lshlrev_b32_e32 v23, 16, v23
	v_pk_fma_f32 v[10:11], v[26:27], v[22:23], v[10:11] op_sel_hi:[0,1,1]
	v_and_b32_e32 v22, 0xffff0000, v24
	v_lshlrev_b32_e32 v23, 16, v24
	v_pk_fma_f32 v[12:13], v[26:27], v[22:23], v[12:13] op_sel_hi:[0,1,1]
	v_and_b32_e32 v22, 0xffff0000, v25
	v_lshlrev_b32_e32 v23, 16, v25
	v_add_f32_e32 v0, v0, v26
	v_pk_fma_f32 v[8:9], v[26:27], v[28:29], v[8:9] op_sel_hi:[0,1,1]
	v_pk_fma_f32 v[14:15], v[26:27], v[22:23], v[14:15] op_sel_hi:[0,1,1]
